# v003 plus: per-lane score maximum in the differential attention loop as a v_max3 tree (16 instead of 36-38 VALU per 64-key half), counted lgkmcnt for the next QK chain
# speedup vs baseline: 1.0137x; 1.0030x over previous
.LBB0_382:
	ds_read_b128 v[2:5], v6 offset:17408
	ds_read_b128 v[8:11], v6 offset:17440
	ds_read_b128 v[12:15], v6 offset:17472
	ds_read_b128 v[128:131], v6 offset:17504
	v_max3_f32 v0, v96, v97, v98
	s_waitcnt lgkmcnt(3)
	v_mfma_f32_32x32x16_bf16 v[112:127], v[2:5], v[156:159], 0
	v_max3_f32 v2, v99, v100, v101
	v_max3_f32 v3, v102, v103, v104
	v_max3_f32 v4, v105, v106, v107
	v_max3_f32 v5, v108, v109, v110
	s_waitcnt lgkmcnt(2)
	v_mfma_f32_32x32x16_bf16 v[112:127], v[8:11], v[152:155], v[112:127]
	v_max3_f32 v0, v0, v2, v3
	v_max3_f32 v2, v111, v80, v81
	v_max3_f32 v3, v82, v83, v84
	v_max3_f32 v7, v85, v86, v87
	s_waitcnt lgkmcnt(1)
	v_mfma_f32_32x32x16_bf16 v[112:127], v[12:15], v[148:151], v[112:127]
	v_max3_f32 v4, v4, v5, v2
	v_max3_f32 v2, v88, v89, v90
	v_max3_f32 v5, v91, v92, v93
	v_max3_f32 v3, v3, v7, v2
	s_waitcnt lgkmcnt(0)
	v_mfma_f32_32x32x16_bf16 v[112:127], v[128:131], v[144:147], v[112:127]
	v_max3_f32 v2, v94, v95, v5
	v_max3_f32 v0, v0, v4, v3
	v_max_f32_e32 v0, v0, v2
	v_mul_f32_e32 v196, s20, v0
	v_pk_add_f32 v[2:3], v[182:183], v[196:197]
	v_mov_b32_e32 v11, v183
	v_cmp_gt_f32_e32 vcc, v2, v3
	s_cbranch_vccz .LBB0_384
	v_and_b32_e32 v4, 64, v228
	v_xor_b32_e32 v2, 32, v228
	v_add_u32_e32 v4, 64, v4
	v_cmp_lt_i32_e32 vcc, v2, v4
	s_nop 1
	v_cndmask_b32_e32 v2, v228, v2, vcc
	v_lshlrev_b32_e32 v2, 2, v2
	ds_bpermute_b32 v2, v2, v0
	v_max_f32_e32 v0, v0, v0
	s_waitcnt lgkmcnt(0)
	v_max_f32_e32 v2, v2, v2
	v_max_f32_e32 v0, v0, v2
	v_fma_f32 v0, s20, v0, v182
	v_cmp_gt_f32_e32 vcc, v0, v3
	s_nop 1
	v_cndmask_b32_e32 v11, v183, v0, vcc

.LBB0_392:
	s_setprio 1
	v_max3_f32 v12, v112, v113, v114
	v_max3_f32 v13, v115, v116, v117
	v_max3_f32 v14, v118, v119, v120
	v_max3_f32 v15, v121, v122, v123
	v_max3_f32 v183, v124, v125, v126
	v_max3_f32 v196, v127, v128, v129
	v_max3_f32 v12, v12, v13, v14
	v_max3_f32 v13, v130, v131, v132
	v_max3_f32 v14, v133, v134, v135
	v_max3_f32 v15, v15, v183, v196
	v_max3_f32 v183, v136, v137, v138
	v_max3_f32 v196, v139, v140, v141
	v_max3_f32 v13, v13, v14, v183
	v_max3_f32 v14, v142, v143, v196
	v_max3_f32 v12, v12, v15, v13
	v_max_f32_e32 v14, v12, v14
	v_mul_f32_e32 v196, s12, v14
	s_waitcnt lgkmcnt(0)
	v_pk_add_f32 v[12:13], v[10:11], v[196:197]
	v_mov_b32_e32 v183, v11
	v_cmp_gt_f32_e32 vcc, v12, v13
	s_cbranch_vccz .LBB0_394
	v_and_b32_e32 v15, 64, v228
	v_xor_b32_e32 v12, 32, v228
	v_add_u32_e32 v15, 64, v15
	v_cmp_lt_i32_e32 vcc, v12, v15
	s_nop 1
	v_cndmask_b32_e32 v12, v228, v12, vcc
	v_lshlrev_b32_e32 v12, 2, v12
	ds_bpermute_b32 v12, v12, v14
	v_max_f32_e32 v14, v14, v14
	s_waitcnt lgkmcnt(0)
	v_max_f32_e32 v12, v12, v12
	v_max_f32_e32 v12, v14, v12
	v_fma_f32 v12, s12, v12, v10
	v_cmp_gt_f32_e32 vcc, v12, v13
	s_nop 1
	v_cndmask_b32_e32 v183, v11, v12, vcc
